# LDS-DMA swizzled double-buffered K-loop for in-proj (ph0) and PEER-scores (ph7) GEMMs
# speedup vs baseline: 1.1721x; 1.1721x over previous
; template <int HOOK>
; __device__ __forceinline__ void gemm_tile(const u16* __restrict__ A, int lda, const u16* __restrict__ B, int ldb, int K, char* smem, const float* ssq = nullptr) {
;     ...
;   u16* sA = (u16*)smem;
;   u16* sB = sA + 128 * 72;
;   const int tid = (threadIdx.x + zz), lane = tid & 63, wave = tid >> 6;
;   const int wm = (wave >> 1) * 64, wn = (wave & 1) * 64;
;   const int lr = lane & 15, lq = lane >> 4;
;   f32x4 acc[4][4];
; #pragma unroll
;   for (int i = 0; i < 4; i++)
; #pragma unroll
;     for (int j = 0; j < 4; j++) acc[i][j] = (f32x4){0.f, 0.f, 0.f, 0.f};
;   u32x4 ra[4], rb[4];
;   float rs[4];
;   if (HOOK) {
; #pragma unroll
;     for (int i = 0; i < 4; i++) {
;       int row = (tid + i * NTHR) >> 3;
;       float4 q = *(const float4*)(ssq + (size_t)row * 4);
;       rs[i] = rsqrtf((q.x + q.y + q.z + q.w) * (1.f / 256.f) + 1e-6f);
;     }
;   }
; #pragma unroll
;   for (int i = 0; i < 4; i++) {
;     int id = tid + i * NTHR; int row = id >> 3, ch = id & 7;
;     ra[i] = *(const u32x4*)(A + (size_t)row * lda + ch * 8);
;     rb[i] = *(const u32x4*)(B + (size_t)row * ldb + ch * 8);
;   }
; #pragma unroll 1
;   for (int k0 = 0; k0 < K; k0 += 64) {
;     __syncthreads();
;     ...
;     int mt = t / ntiles, nt = t % ntiles;
;     int m0 = mt * 128, n0 = nt * 128;
;     gemm_tile<(EPI == EPI_OUT) ? 1 : 0>(A + (size_t)m0 * lda, lda, Bt + (size_t)n0 * ldb, ldb, K, smem, (const float*)(p.ws + zz + O_SSQ) + (size_t)m0 * 4);
.LBB0_778:
	s_ashr_i32 s0, s11, 31
	s_lshr_b32 s0, s0, 28
	s_add_i32 s0, s11, s0
	s_and_b32 s1, s0, 0x1fffff0
	s_lshl_b32 s0, s0, 3
	s_and_b32 s2, s0, 0xffffff80
	s_sub_i32 s1, s11, s1
	s_ashr_i32 s3, s2, 31
	s_lshl_b32 s6, s1, 7
	s_lshl_b64 s[0:1], s[2:3], 11
	s_add_u32 s8, s12, s0
	s_addc_u32 s9, s13, s1
	s_ashr_i32 s7, s6, 31
	s_mov_b32 s3, 0
	s_lshl_b64 s[24:25], s[6:7], 11
	v_add_u32_e32 v122, s3, v128
	s_waitcnt vmcnt(3)
	v_add_u32_e32 v8, 0x100, v122
	s_waitcnt vmcnt(2)
	v_add_u32_e32 v16, 0x200, v122
	s_waitcnt vmcnt(0)
	v_add_u32_e32 v28, 0x300, v122
	s_add_u32 s26, s14, s24
	v_lshlrev_b32_e32 v0, 4, v122
	v_ashrrev_i32_e32 v36, 3, v122
	v_ashrrev_i32_e32 v40, 3, v8
	s_waitcnt vmcnt(0)
	v_ashrrev_i32_e32 v44, 3, v16
	v_ashrrev_i32_e32 v48, 3, v28
	s_addc_u32 s27, s15, s25
	v_and_b32_e32 v132, 0x70, v0
	v_ashrrev_i32_e32 v37, 31, v36
	v_ashrrev_i32_e32 v41, 31, v40
	v_ashrrev_i32_e32 v45, 31, v44
	v_ashrrev_i32_e32 v49, 31, v48
	v_lshl_add_u64 v[24:25], s[8:9], 0, v[132:133]
	v_lshl_add_u64 v[26:27], s[26:27], 0, v[132:133]
	v_lshlrev_b64 v[38:39], 11, v[36:37]
	v_lshlrev_b64 v[42:43], 11, v[40:41]
	v_lshlrev_b64 v[46:47], 11, v[44:45]
	v_lshlrev_b64 v[50:51], 11, v[48:49]
	v_lshl_add_u64 v[0:1], v[24:25], 0, v[38:39]
	v_lshl_add_u64 v[4:5], v[26:27], 0, v[38:39]
	v_lshl_add_u64 v[8:9], v[24:25], 0, v[42:43]
	v_lshl_add_u64 v[12:13], v[26:27], 0, v[42:43]
	v_lshl_add_u64 v[16:17], v[24:25], 0, v[46:47]
	v_lshl_add_u64 v[20:21], v[26:27], 0, v[46:47]
	v_lshl_add_u64 v[24:25], v[24:25], 0, v[50:51]
	v_lshl_add_u64 v[26:27], v[26:27], 0, v[50:51]
	v_ashrrev_i32_e32 v52, 1, v122
	v_and_b32_e32 v123, 15, v122
	v_and_b32_e32 v124, 0xffffffc0, v52
	s_add_u32 s0, s19, s0
	v_or_b32_e32 v24, v124, v123
	s_addc_u32 s1, s20, s1
	v_bfe_u32 v125, v122, 4, 2
	v_and_b32_e32 v26, 0x4f, v122
	v_mul_lo_u32 v27, v24, s33
	v_and_b32_e32 v24, 7, v122
	v_lshl_add_u64 v[104:105], s[0:1], 0, v[38:39]
	v_lshl_add_u64 v[106:107], s[0:1], 0, v[42:43]
	v_lshl_add_u64 v[108:109], s[0:1], 0, v[46:47]
	v_lshl_add_u64 v[110:111], s[0:1], 0, v[50:51]
	s_add_u32 s0, s21, s24
	v_lshlrev_b32_e32 v25, 4, v125
	v_mad_u64_u32 v[96:97], s[8:9], v36, s33, v[132:133]
	v_mad_u64_u32 v[98:99], s[8:9], v40, s33, v[132:133]
	v_mad_u64_u32 v[100:101], s[8:9], v44, s33, v[132:133]
	v_mad_u64_u32 v[102:103], s[8:9], v48, s33, v[132:133]
	v_mul_u32_u24_e32 v26, 0x90, v26
	v_lshlrev_b32_e32 v132, 4, v24
	s_addc_u32 s1, s22, s25
	v_mov_b32_e32 v24, 0
	v_lshl_add_u64 v[112:113], s[0:1], 0, v[38:39]
	v_lshl_add_u64 v[114:115], s[0:1], 0, v[42:43]
	v_lshl_add_u64 v[116:117], s[0:1], 0, v[46:47]
	v_lshl_add_u64 v[118:119], s[0:1], 0, v[50:51]
	s_mov_b32 s3, 0
	v_add_u32_e32 v97, v25, v27
	v_add_u32_e32 v99, v25, v26
	v_mov_b32_e32 v25, v24
	v_mov_b32_e32 v26, v24
	v_mov_b32_e32 v27, v24
	v_mov_b32_e32 v36, v24
	v_mov_b32_e32 v37, v24
	v_mov_b32_e32 v38, v24
	v_mov_b32_e32 v39, v24
	v_mov_b32_e32 v40, v24
	v_mov_b32_e32 v41, v24
	v_mov_b32_e32 v42, v24
	v_mov_b32_e32 v43, v24
	v_mov_b32_e32 v44, v24
	v_mov_b32_e32 v45, v24
	v_mov_b32_e32 v46, v24
	v_mov_b32_e32 v47, v24
	v_mov_b32_e32 v48, v24
	v_mov_b32_e32 v49, v24
	v_mov_b32_e32 v50, v24
	v_mov_b32_e32 v51, v24
	v_mov_b32_e32 v52, v24
	v_mov_b32_e32 v53, v24
	v_mov_b32_e32 v54, v24
	v_mov_b32_e32 v55, v24
	v_mov_b32_e32 v56, v24
	v_mov_b32_e32 v57, v24
	v_mov_b32_e32 v58, v24
	v_mov_b32_e32 v59, v24
	v_mov_b32_e32 v60, v24
	v_mov_b32_e32 v61, v24
	v_mov_b32_e32 v62, v24
	v_mov_b32_e32 v63, v24
	v_mov_b32_e32 v64, v24
	v_mov_b32_e32 v65, v24
	v_mov_b32_e32 v66, v24
	v_mov_b32_e32 v67, v24
	v_mov_b32_e32 v68, v24
	v_mov_b32_e32 v69, v24
	v_mov_b32_e32 v70, v24
	v_mov_b32_e32 v71, v24
	v_mov_b32_e32 v72, v24
	v_mov_b32_e32 v73, v24
	v_mov_b32_e32 v74, v24
	v_mov_b32_e32 v75, v24
	v_mov_b32_e32 v76, v24
	v_mov_b32_e32 v77, v24
	v_mov_b32_e32 v78, v24
	v_mov_b32_e32 v79, v24
	v_mov_b32_e32 v80, v24
	v_mov_b32_e32 v81, v24
	v_mov_b32_e32 v82, v24
	v_mov_b32_e32 v83, v24
	v_mov_b32_e32 v84, v24
	v_mov_b32_e32 v85, v24
	v_mov_b32_e32 v86, v24
	v_mov_b32_e32 v87, v24
	v_mov_b32_e32 v88, v24
	v_mov_b32_e32 v89, v24
	v_mov_b32_e32 v90, v24
	v_mov_b32_e32 v91, v24
	v_mov_b32_e32 v92, v24
	v_mov_b32_e32 v93, v24
	v_mov_b32_e32 v94, v24
	v_mov_b32_e32 v95, v24
	v_lshrrev_b32_e32 v208, 3, v122
	v_xor_b32_e32 v208, v208, v122
	v_and_b32_e32 v208, 7, v208
	v_lshlrev_b32_e32 v208, 4, v208
	v_add_u32_e32 v208, 0xffffff80, v208
	v_mov_b32_e32 v209, -1
	v_lshl_add_u64 v[104:105], v[104:105], 0, v[208:209]
	v_lshl_add_u64 v[106:107], v[106:107], 0, v[208:209]
	v_lshl_add_u64 v[108:109], v[108:109], 0, v[208:209]
	v_lshl_add_u64 v[110:111], v[110:111], 0, v[208:209]
	v_lshl_add_u64 v[112:113], v[112:113], 0, v[208:209]
	v_lshl_add_u64 v[114:115], v[114:115], 0, v[208:209]
	v_lshl_add_u64 v[116:117], v[116:117], 0, v[208:209]
	v_lshl_add_u64 v[118:119], v[118:119], 0, v[208:209]
	v_and_b32_e32 v204, 7, v123
	v_xor_b32_e32 v204, v204, v125
	v_lshlrev_b32_e32 v204, 4, v204
	v_or_b32_e32 v206, v124, v123
	v_lshl_add_u32 v205, v206, 7, v204
	v_and_b32_e32 v206, 0x4f, v122
	v_lshl_add_u32 v206, v206, 7, v204
	v_xor_b32_e32 v207, 64, v206
	v_xor_b32_e32 v204, 64, v205
	v_lshrrev_b32_e32 v208, 6, v122
	s_nop 1
	v_readfirstlane_b32 s56, v208
	s_nop 3
	s_lshl_b32 s56, s56, 10
	s_waitcnt lgkmcnt(0)
	s_barrier
	s_mov_b32 m0, s56
	s_nop 0
	global_load_lds_dwordx4 v[104:105], off
	s_add_u32 m0, s56, 0x1000
	s_nop 0
	global_load_lds_dwordx4 v[106:107], off
	s_add_u32 m0, s56, 0x2000
	s_nop 0
	global_load_lds_dwordx4 v[108:109], off
	s_add_u32 m0, s56, 0x3000
	s_nop 0
	global_load_lds_dwordx4 v[110:111], off
	s_add_u32 m0, s56, 0x4000
	s_nop 0
	global_load_lds_dwordx4 v[112:113], off
	s_add_u32 m0, s56, 0x5000
	s_nop 0
	global_load_lds_dwordx4 v[114:115], off
	s_add_u32 m0, s56, 0x6000
	s_nop 0
	global_load_lds_dwordx4 v[116:117], off
	s_add_u32 m0, s56, 0x7000
	s_nop 0
	global_load_lds_dwordx4 v[118:119], off
	v_lshl_add_u64 v[104:105], v[104:105], 0, s[30:31]
	v_lshl_add_u64 v[106:107], v[106:107], 0, s[30:31]
	v_lshl_add_u64 v[108:109], v[108:109], 0, s[30:31]
	v_lshl_add_u64 v[110:111], v[110:111], 0, s[30:31]
	v_lshl_add_u64 v[112:113], v[112:113], 0, s[30:31]
	v_lshl_add_u64 v[114:115], v[114:115], 0, s[30:31]
	v_lshl_add_u64 v[116:117], v[116:117], 0, s[30:31]
	v_lshl_add_u64 v[118:119], v[118:119], 0, s[30:31]
	s_waitcnt vmcnt(0)
	s_barrier
; DEV f32x4 mfma16(bf16x8 a, bf16x8 b, f32x4 c) { return __builtin_amdgcn_mfma_f32_16x16x32_bf16(a, b, c, 0, 0, 0); }
; template <int HOOK>
; __device__ __forceinline__ void gemm_tile(const u16* __restrict__ A, int lda, const u16* __restrict__ B, int ldb, int K, char* smem, const float* ssq = nullptr) {
;     ...
;   for (int k0 = 0; k0 < K; k0 += 64) {
;     __syncthreads();
;     if (HOOK && k0 >= 512 && k0 < 768) {
; #pragma unroll
;       for (int i = 0; i < 4; i++) {
;         float t8[8];
;         unpack8(ra[i], t8);
; #pragma unroll
;         for (int e = 0; e < 8; e++) t8[e] *= rs[i];
;         ra[i] = pack8(t8);
;       }
;     }
; #pragma unroll
;     for (int i = 0; i < 4; i++) {
;       int id = tid + i * NTHR; int row = id >> 3, ch = id & 7;
;       *(u32x4*)(sA + row * 72 + ch * 8) = ra[i];
;       *(u32x4*)(sB + row * 72 + ch * 8) = rb[i];
;     }
;     __syncthreads();
;     if (k0 + 64 < K) {
; #pragma unroll
;       for (int i = 0; i < 4; i++) {
;         int id = tid + i * NTHR; int row = id >> 3, ch = id & 7;
;         ra[i] = *(const u32x4*)(A + (size_t)row * lda + k0 + 64 + ch * 8);
;         rb[i] = *(const u32x4*)(B + (size_t)row * ldb + k0 + 64 + ch * 8);
;       }
;     }
; #pragma unroll
;     for (int kk = 0; kk < 64; kk += 32) {
;       bf16x8 af[4], bfr[4];
; #pragma unroll
;       for (int i = 0; i < 4; i++) af[i] = *(const bf16x8*)(sA + (wm + i * 16 + lr) * 72 + kk + lq * 8);
; #pragma unroll
;       for (int j = 0; j < 4; j++) bfr[j] = *(const bf16x8*)(sB + (wn + j * 16 + lr) * 72 + kk + lq * 8);
;       __builtin_amdgcn_s_setprio(1);
; #pragma unroll
;       for (int i = 0; i < 4; i++)
; #pragma unroll
;         for (int j = 0; j < 4; j++) acc[i][j] = mfma16(af[i], bfr[j], acc[i][j]);
;       __builtin_amdgcn_s_setprio(0);
;     }
.Ldp7_loop:
	ds_read_b128 v[140:143], v205 offset:0
	ds_read_b128 v[144:147], v205 offset:2048
	ds_read_b128 v[148:151], v205 offset:4096
	ds_read_b128 v[152:155], v205 offset:6144
	ds_read_b128 v[156:159], v206 offset:16384
	ds_read_b128 v[160:163], v206 offset:18432
	ds_read_b128 v[164:167], v206 offset:20480
	ds_read_b128 v[168:171], v206 offset:22528
	s_add_u32 m0, s56, 0x8000
	s_nop 0
	global_load_lds_dwordx4 v[104:105], off
	s_add_u32 m0, s56, 0x9000
	s_nop 0
	global_load_lds_dwordx4 v[106:107], off
	s_add_u32 m0, s56, 0xa000
	s_nop 0
	global_load_lds_dwordx4 v[108:109], off
	s_add_u32 m0, s56, 0xb000
	s_nop 0
	global_load_lds_dwordx4 v[110:111], off
	s_add_u32 m0, s56, 0xc000
	s_nop 0
	global_load_lds_dwordx4 v[112:113], off
	s_add_u32 m0, s56, 0xd000
	s_nop 0
	global_load_lds_dwordx4 v[114:115], off
	s_add_u32 m0, s56, 0xe000
	s_nop 0
	global_load_lds_dwordx4 v[116:117], off
	s_add_u32 m0, s56, 0xf000
	s_nop 0
	global_load_lds_dwordx4 v[118:119], off
	s_setprio 1
	s_waitcnt lgkmcnt(3)
	v_mfma_f32_16x16x32_bf16 v[92:95], v[140:143], v[156:159], v[92:95]
	s_waitcnt lgkmcnt(2)
	v_mfma_f32_16x16x32_bf16 v[88:91], v[140:143], v[160:163], v[88:91]
	s_waitcnt lgkmcnt(1)
	v_mfma_f32_16x16x32_bf16 v[84:87], v[140:143], v[164:167], v[84:87]
	s_waitcnt lgkmcnt(0)
	v_mfma_f32_16x16x32_bf16 v[80:83], v[140:143], v[168:171], v[80:83]
	ds_read_b128 v[172:175], v204 offset:0
	ds_read_b128 v[176:179], v204 offset:2048
	ds_read_b128 v[180:183], v204 offset:4096
	ds_read_b128 v[184:187], v204 offset:6144
	ds_read_b128 v[188:191], v207 offset:16384
	ds_read_b128 v[192:195], v207 offset:18432
	ds_read_b128 v[196:199], v207 offset:20480
	ds_read_b128 v[200:203], v207 offset:22528
	v_mfma_f32_16x16x32_bf16 v[76:79], v[144:147], v[156:159], v[76:79]
	v_lshl_add_u64 v[104:105], v[104:105], 0, s[30:31]
	v_mfma_f32_16x16x32_bf16 v[72:75], v[144:147], v[160:163], v[72:75]
	v_lshl_add_u64 v[106:107], v[106:107], 0, s[30:31]
	v_mfma_f32_16x16x32_bf16 v[68:71], v[144:147], v[164:167], v[68:71]
	v_lshl_add_u64 v[108:109], v[108:109], 0, s[30:31]
	v_mfma_f32_16x16x32_bf16 v[64:67], v[144:147], v[168:171], v[64:67]
	v_lshl_add_u64 v[110:111], v[110:111], 0, s[30:31]
	v_mfma_f32_16x16x32_bf16 v[60:63], v[148:151], v[156:159], v[60:63]
	v_lshl_add_u64 v[112:113], v[112:113], 0, s[30:31]
	v_mfma_f32_16x16x32_bf16 v[56:59], v[148:151], v[160:163], v[56:59]
	v_lshl_add_u64 v[114:115], v[114:115], 0, s[30:31]
	v_mfma_f32_16x16x32_bf16 v[52:55], v[148:151], v[164:167], v[52:55]
	v_lshl_add_u64 v[116:117], v[116:117], 0, s[30:31]
	v_mfma_f32_16x16x32_bf16 v[48:51], v[148:151], v[168:171], v[48:51]
	v_lshl_add_u64 v[118:119], v[118:119], 0, s[30:31]
	v_mfma_f32_16x16x32_bf16 v[44:47], v[152:155], v[156:159], v[44:47]
	v_mfma_f32_16x16x32_bf16 v[40:43], v[152:155], v[160:163], v[40:43]
	v_mfma_f32_16x16x32_bf16 v[36:39], v[152:155], v[164:167], v[36:39]
	v_mfma_f32_16x16x32_bf16 v[24:27], v[152:155], v[168:171], v[24:27]
	s_waitcnt lgkmcnt(3)
	v_mfma_f32_16x16x32_bf16 v[92:95], v[172:175], v[188:191], v[92:95]
	s_waitcnt lgkmcnt(2)
	v_mfma_f32_16x16x32_bf16 v[88:91], v[172:175], v[192:195], v[88:91]
	s_waitcnt lgkmcnt(1)
	v_mfma_f32_16x16x32_bf16 v[84:87], v[172:175], v[196:199], v[84:87]
	s_waitcnt lgkmcnt(0)
	v_mfma_f32_16x16x32_bf16 v[80:83], v[172:175], v[200:203], v[80:83]
	v_mfma_f32_16x16x32_bf16 v[76:79], v[176:179], v[188:191], v[76:79]
	v_mfma_f32_16x16x32_bf16 v[72:75], v[176:179], v[192:195], v[72:75]
	v_mfma_f32_16x16x32_bf16 v[68:71], v[176:179], v[196:199], v[68:71]
	v_mfma_f32_16x16x32_bf16 v[64:67], v[176:179], v[200:203], v[64:67]
	v_mfma_f32_16x16x32_bf16 v[60:63], v[180:183], v[188:191], v[60:63]
	v_mfma_f32_16x16x32_bf16 v[56:59], v[180:183], v[192:195], v[56:59]
	v_mfma_f32_16x16x32_bf16 v[52:55], v[180:183], v[196:199], v[52:55]
	v_mfma_f32_16x16x32_bf16 v[48:51], v[180:183], v[200:203], v[48:51]
	v_mfma_f32_16x16x32_bf16 v[44:47], v[184:187], v[188:191], v[44:47]
	v_mfma_f32_16x16x32_bf16 v[40:43], v[184:187], v[192:195], v[40:43]
	v_mfma_f32_16x16x32_bf16 v[36:39], v[184:187], v[196:199], v[36:39]
	v_mfma_f32_16x16x32_bf16 v[24:27], v[184:187], v[200:203], v[24:27]
	s_setprio 0
	s_waitcnt vmcnt(0)
	s_barrier
	s_add_i32 s3, s3, 0x80
	ds_read_b128 v[140:143], v205 offset:32768
	ds_read_b128 v[144:147], v205 offset:34816
	ds_read_b128 v[148:151], v205 offset:36864
	ds_read_b128 v[152:155], v205 offset:38912
	ds_read_b128 v[156:159], v206 offset:49152
	ds_read_b128 v[160:163], v206 offset:51200
	ds_read_b128 v[164:167], v206 offset:53248
	ds_read_b128 v[168:171], v206 offset:55296
	s_cmpk_lt_u32 s3, 0x400
	s_cbranch_scc0 .Ldp7_nodma
	s_mov_b32 m0, s56
	s_nop 0
	global_load_lds_dwordx4 v[104:105], off
	s_add_u32 m0, s56, 0x1000
	s_nop 0
	global_load_lds_dwordx4 v[106:107], off
	s_add_u32 m0, s56, 0x2000
	s_nop 0
	global_load_lds_dwordx4 v[108:109], off
	s_add_u32 m0, s56, 0x3000
	s_nop 0
	global_load_lds_dwordx4 v[110:111], off
	s_add_u32 m0, s56, 0x4000
	s_nop 0
	global_load_lds_dwordx4 v[112:113], off
	s_add_u32 m0, s56, 0x5000
	s_nop 0
	global_load_lds_dwordx4 v[114:115], off
	s_add_u32 m0, s56, 0x6000
	s_nop 0
	global_load_lds_dwordx4 v[116:117], off
	s_add_u32 m0, s56, 0x7000
	s_nop 0
	global_load_lds_dwordx4 v[118:119], off
; DEV f32x4 mfma16(bf16x8 a, bf16x8 b, f32x4 c) { return __builtin_amdgcn_mfma_f32_16x16x32_bf16(a, b, c, 0, 0, 0); }
; template <int HOOK>
; __device__ __forceinline__ void gemm_tile(const u16* __restrict__ A, int lda, const u16* __restrict__ B, int ldb, int K, char* smem, const float* ssq = nullptr) {
;     ...
;   for (int k0 = 0; k0 < K; k0 += 64) {
;     __syncthreads();
;     if (HOOK && k0 >= 512 && k0 < 768) {
; #pragma unroll
;       for (int i = 0; i < 4; i++) {
;         float t8[8];
;         unpack8(ra[i], t8);
; #pragma unroll
;         for (int e = 0; e < 8; e++) t8[e] *= rs[i];
;         ra[i] = pack8(t8);
;       }
;     }
; #pragma unroll
;     for (int i = 0; i < 4; i++) {
;       int id = tid + i * NTHR; int row = id >> 3, ch = id & 7;
;       *(u32x4*)(sA + row * 72 + ch * 8) = ra[i];
;       *(u32x4*)(sB + row * 72 + ch * 8) = rb[i];
;     }
;     __syncthreads();
;     if (k0 + 64 < K) {
; #pragma unroll
;       for (int i = 0; i < 4; i++) {
;         int id = tid + i * NTHR; int row = id >> 3, ch = id & 7;
;         ra[i] = *(const u32x4*)(A + (size_t)row * lda + k0 + 64 + ch * 8);
;         rb[i] = *(const u32x4*)(B + (size_t)row * ldb + k0 + 64 + ch * 8);
;       }
;     }
; #pragma unroll
;     for (int kk = 0; kk < 64; kk += 32) {
;       bf16x8 af[4], bfr[4];
; #pragma unroll
;       for (int i = 0; i < 4; i++) af[i] = *(const bf16x8*)(sA + (wm + i * 16 + lr) * 72 + kk + lq * 8);
; #pragma unroll
;       for (int j = 0; j < 4; j++) bfr[j] = *(const bf16x8*)(sB + (wn + j * 16 + lr) * 72 + kk + lq * 8);
;       __builtin_amdgcn_s_setprio(1);
; #pragma unroll
;       for (int i = 0; i < 4; i++)
; #pragma unroll
;         for (int j = 0; j < 4; j++) acc[i][j] = mfma16(af[i], bfr[j], acc[i][j]);
;       __builtin_amdgcn_s_setprio(0);
;     }
.Ldp7_nodma:
	s_setprio 1
	s_waitcnt lgkmcnt(3)
	v_mfma_f32_16x16x32_bf16 v[92:95], v[140:143], v[156:159], v[92:95]
	s_waitcnt lgkmcnt(2)
	v_mfma_f32_16x16x32_bf16 v[88:91], v[140:143], v[160:163], v[88:91]
	s_waitcnt lgkmcnt(1)
	v_mfma_f32_16x16x32_bf16 v[84:87], v[140:143], v[164:167], v[84:87]
	s_waitcnt lgkmcnt(0)
	v_mfma_f32_16x16x32_bf16 v[80:83], v[140:143], v[168:171], v[80:83]
	ds_read_b128 v[172:175], v204 offset:32768
	ds_read_b128 v[176:179], v204 offset:34816
	ds_read_b128 v[180:183], v204 offset:36864
	ds_read_b128 v[184:187], v204 offset:38912
	ds_read_b128 v[188:191], v207 offset:49152
	ds_read_b128 v[192:195], v207 offset:51200
	ds_read_b128 v[196:199], v207 offset:53248
	ds_read_b128 v[200:203], v207 offset:55296
	v_mfma_f32_16x16x32_bf16 v[76:79], v[144:147], v[156:159], v[76:79]
	v_lshl_add_u64 v[104:105], v[104:105], 0, s[30:31]
	v_mfma_f32_16x16x32_bf16 v[72:75], v[144:147], v[160:163], v[72:75]
	v_lshl_add_u64 v[106:107], v[106:107], 0, s[30:31]
	v_mfma_f32_16x16x32_bf16 v[68:71], v[144:147], v[164:167], v[68:71]
	v_lshl_add_u64 v[108:109], v[108:109], 0, s[30:31]
	v_mfma_f32_16x16x32_bf16 v[64:67], v[144:147], v[168:171], v[64:67]
	v_lshl_add_u64 v[110:111], v[110:111], 0, s[30:31]
	v_mfma_f32_16x16x32_bf16 v[60:63], v[148:151], v[156:159], v[60:63]
	v_lshl_add_u64 v[112:113], v[112:113], 0, s[30:31]
	v_mfma_f32_16x16x32_bf16 v[56:59], v[148:151], v[160:163], v[56:59]
	v_lshl_add_u64 v[114:115], v[114:115], 0, s[30:31]
	v_mfma_f32_16x16x32_bf16 v[52:55], v[148:151], v[164:167], v[52:55]
	v_lshl_add_u64 v[116:117], v[116:117], 0, s[30:31]
	v_mfma_f32_16x16x32_bf16 v[48:51], v[148:151], v[168:171], v[48:51]
	v_lshl_add_u64 v[118:119], v[118:119], 0, s[30:31]
	v_mfma_f32_16x16x32_bf16 v[44:47], v[152:155], v[156:159], v[44:47]
	v_mfma_f32_16x16x32_bf16 v[40:43], v[152:155], v[160:163], v[40:43]
	v_mfma_f32_16x16x32_bf16 v[36:39], v[152:155], v[164:167], v[36:39]
	v_mfma_f32_16x16x32_bf16 v[24:27], v[152:155], v[168:171], v[24:27]
	s_waitcnt lgkmcnt(3)
	v_mfma_f32_16x16x32_bf16 v[92:95], v[172:175], v[188:191], v[92:95]
	s_waitcnt lgkmcnt(2)
	v_mfma_f32_16x16x32_bf16 v[88:91], v[172:175], v[192:195], v[88:91]
	s_waitcnt lgkmcnt(1)
	v_mfma_f32_16x16x32_bf16 v[84:87], v[172:175], v[196:199], v[84:87]
	s_waitcnt lgkmcnt(0)
	v_mfma_f32_16x16x32_bf16 v[80:83], v[172:175], v[200:203], v[80:83]
	v_mfma_f32_16x16x32_bf16 v[76:79], v[176:179], v[188:191], v[76:79]
	v_mfma_f32_16x16x32_bf16 v[72:75], v[176:179], v[192:195], v[72:75]
	v_mfma_f32_16x16x32_bf16 v[68:71], v[176:179], v[196:199], v[68:71]
	v_mfma_f32_16x16x32_bf16 v[64:67], v[176:179], v[200:203], v[64:67]
	v_mfma_f32_16x16x32_bf16 v[60:63], v[180:183], v[188:191], v[60:63]
	v_mfma_f32_16x16x32_bf16 v[56:59], v[180:183], v[192:195], v[56:59]
	v_mfma_f32_16x16x32_bf16 v[52:55], v[180:183], v[196:199], v[52:55]
	v_mfma_f32_16x16x32_bf16 v[48:51], v[180:183], v[200:203], v[48:51]
	v_mfma_f32_16x16x32_bf16 v[44:47], v[184:187], v[188:191], v[44:47]
	v_mfma_f32_16x16x32_bf16 v[40:43], v[184:187], v[192:195], v[40:43]
	v_mfma_f32_16x16x32_bf16 v[36:39], v[184:187], v[196:199], v[36:39]
	v_mfma_f32_16x16x32_bf16 v[24:27], v[184:187], v[200:203], v[24:27]
	s_setprio 0
	s_waitcnt vmcnt(0)
	s_barrier
	s_cmpk_lt_u32 s3, 0x400
	s_cbranch_scc1 .Ldp7_loop

; template <int HOOK>
; __device__ __forceinline__ void gemm_tile(const u16* __restrict__ A, int lda, const u16* __restrict__ B, int ldb, int K, char* smem, const float* ssq = nullptr) {
;     ...
;   u16* sA = (u16*)smem;
;   u16* sB = sA + 128 * 72;
;   const int tid = (threadIdx.x + zz), lane = tid & 63, wave = tid >> 6;
;   const int wm = (wave >> 1) * 64, wn = (wave & 1) * 64;
;   const int lr = lane & 15, lq = lane >> 4;
;   f32x4 acc[4][4];
; #pragma unroll
;   for (int i = 0; i < 4; i++)
; #pragma unroll
;     for (int j = 0; j < 4; j++) acc[i][j] = (f32x4){0.f, 0.f, 0.f, 0.f};
;   u32x4 ra[4], rb[4];
;   float rs[4];
;   if (HOOK) {
; #pragma unroll
;     for (int i = 0; i < 4; i++) {
;       int row = (tid + i * NTHR) >> 3;
;       float4 q = *(const float4*)(ssq + (size_t)row * 4);
;       rs[i] = rsqrtf((q.x + q.y + q.z + q.w) * (1.f / 256.f) + 1e-6f);
;     }
;   }
; #pragma unroll
;   for (int i = 0; i < 4; i++) {
;     int id = tid + i * NTHR; int row = id >> 3, ch = id & 7;
;     ra[i] = *(const u32x4*)(A + (size_t)row * lda + ch * 8);
;     rb[i] = *(const u32x4*)(B + (size_t)row * ldb + ch * 8);
;   }
; #pragma unroll 1
;   for (int k0 = 0; k0 < K; k0 += 64) {
;     __syncthreads();
;     ...
;     int mt = t / ntiles, nt = t % ntiles;
;     int m0 = mt * 128, n0 = nt * 128;
;     gemm_tile<(EPI == EPI_OUT) ? 1 : 0>(A + (size_t)m0 * lda, lda, Bt + (size_t)n0 * ldb, ldb, K, smem, (const float*)(p.ws + zz + O_SSQ) + (size_t)m0 * 4);
.LBB0_1458:
	s_mul_hi_i32 s0, s10, 0x2aaaaaab
	s_lshr_b32 s1, s0, 31
	s_ashr_i32 s0, s0, 2
	s_add_i32 s0, s0, s1
	s_mul_i32 s1, s0, 24
	s_lshl_b32 s2, s0, 7
	s_sub_i32 s1, s10, s1
	s_ashr_i32 s3, s2, 31
	s_lshl_b32 s6, s1, 7
	s_lshl_b64 s[0:1], s[2:3], 11
	s_add_u32 s8, s11, s0
	s_addc_u32 s9, s12, s1
	s_ashr_i32 s7, s6, 31
	s_mov_b32 s3, 0
	s_lshl_b64 s[22:23], s[6:7], 11
	v_add_u32_e32 v122, s3, v128
	s_waitcnt vmcnt(3)
	v_add_u32_e32 v8, 0x100, v122
	s_waitcnt vmcnt(2)
	v_add_u32_e32 v16, 0x200, v122
	s_waitcnt vmcnt(0)
	v_add_u32_e32 v28, 0x300, v122
	s_add_u32 s24, s13, s22
	v_lshlrev_b32_e32 v0, 4, v122
	v_ashrrev_i32_e32 v36, 3, v122
	v_ashrrev_i32_e32 v40, 3, v8
	v_ashrrev_i32_e32 v44, 3, v16
	v_ashrrev_i32_e32 v48, 3, v28
	s_addc_u32 s25, s14, s23
	v_and_b32_e32 v132, 0x70, v0
	v_ashrrev_i32_e32 v37, 31, v36
	v_ashrrev_i32_e32 v41, 31, v40
	v_ashrrev_i32_e32 v45, 31, v44
	v_ashrrev_i32_e32 v49, 31, v48
	v_lshl_add_u64 v[24:25], s[8:9], 0, v[132:133]
	v_lshl_add_u64 v[26:27], s[24:25], 0, v[132:133]
	v_lshlrev_b64 v[38:39], 11, v[36:37]
	v_lshlrev_b64 v[42:43], 11, v[40:41]
	v_lshlrev_b64 v[46:47], 11, v[44:45]
	v_lshlrev_b64 v[50:51], 11, v[48:49]
	v_lshl_add_u64 v[0:1], v[24:25], 0, v[38:39]
	v_lshl_add_u64 v[4:5], v[26:27], 0, v[38:39]
	v_lshl_add_u64 v[8:9], v[24:25], 0, v[42:43]
	v_lshl_add_u64 v[12:13], v[26:27], 0, v[42:43]
	v_lshl_add_u64 v[16:17], v[24:25], 0, v[46:47]
	v_lshl_add_u64 v[20:21], v[26:27], 0, v[46:47]
	v_lshl_add_u64 v[24:25], v[24:25], 0, v[50:51]
	v_lshl_add_u64 v[26:27], v[26:27], 0, v[50:51]
	v_ashrrev_i32_e32 v52, 1, v122
	v_and_b32_e32 v123, 15, v122
	v_and_b32_e32 v124, 0xffffffc0, v52
	s_add_u32 s0, s18, s0
	v_or_b32_e32 v24, v124, v123
	s_addc_u32 s1, s19, s1
	v_bfe_u32 v125, v122, 4, 2
	v_and_b32_e32 v26, 0x4f, v122
	v_mul_lo_u32 v27, v24, s33
	v_and_b32_e32 v24, 7, v122
	v_lshl_add_u64 v[104:105], s[0:1], 0, v[38:39]
	v_lshl_add_u64 v[106:107], s[0:1], 0, v[42:43]
	v_lshl_add_u64 v[108:109], s[0:1], 0, v[46:47]
	v_lshl_add_u64 v[110:111], s[0:1], 0, v[50:51]
	s_add_u32 s0, s20, s22
	v_lshlrev_b32_e32 v25, 4, v125
	v_mad_u64_u32 v[96:97], s[8:9], v36, s33, v[132:133]
	v_mad_u64_u32 v[98:99], s[8:9], v40, s33, v[132:133]
	v_mad_u64_u32 v[100:101], s[8:9], v44, s33, v[132:133]
	v_mad_u64_u32 v[102:103], s[8:9], v48, s33, v[132:133]
	v_mul_u32_u24_e32 v26, 0x90, v26
	v_lshlrev_b32_e32 v132, 4, v24
	s_addc_u32 s1, s21, s23
	v_mov_b32_e32 v24, 0
	v_lshl_add_u64 v[112:113], s[0:1], 0, v[38:39]
	v_lshl_add_u64 v[114:115], s[0:1], 0, v[42:43]
	v_lshl_add_u64 v[116:117], s[0:1], 0, v[46:47]
	v_lshl_add_u64 v[118:119], s[0:1], 0, v[50:51]
	s_mov_b32 s3, 0
	v_add_u32_e32 v97, v25, v27
	v_add_u32_e32 v99, v25, v26
	v_mov_b32_e32 v25, v24
	v_mov_b32_e32 v26, v24
	v_mov_b32_e32 v27, v24
	v_mov_b32_e32 v36, v24
	v_mov_b32_e32 v37, v24
	v_mov_b32_e32 v38, v24
	v_mov_b32_e32 v39, v24
	v_mov_b32_e32 v40, v24
	v_mov_b32_e32 v41, v24
	v_mov_b32_e32 v42, v24
	v_mov_b32_e32 v43, v24
	v_mov_b32_e32 v44, v24
	v_mov_b32_e32 v45, v24
	v_mov_b32_e32 v46, v24
	v_mov_b32_e32 v47, v24
	v_mov_b32_e32 v48, v24
	v_mov_b32_e32 v49, v24
	v_mov_b32_e32 v50, v24
	v_mov_b32_e32 v51, v24
	v_mov_b32_e32 v52, v24
	v_mov_b32_e32 v53, v24
	v_mov_b32_e32 v54, v24
	v_mov_b32_e32 v55, v24
	v_mov_b32_e32 v56, v24
	v_mov_b32_e32 v57, v24
	v_mov_b32_e32 v58, v24
	v_mov_b32_e32 v59, v24
	v_mov_b32_e32 v60, v24
	v_mov_b32_e32 v61, v24
	v_mov_b32_e32 v62, v24
	v_mov_b32_e32 v63, v24
	v_mov_b32_e32 v64, v24
	v_mov_b32_e32 v65, v24
	v_mov_b32_e32 v66, v24
	v_mov_b32_e32 v67, v24
	v_mov_b32_e32 v68, v24
	v_mov_b32_e32 v69, v24
	v_mov_b32_e32 v70, v24
	v_mov_b32_e32 v71, v24
	v_mov_b32_e32 v72, v24
	v_mov_b32_e32 v73, v24
	v_mov_b32_e32 v74, v24
	v_mov_b32_e32 v75, v24
	v_mov_b32_e32 v76, v24
	v_mov_b32_e32 v77, v24
	v_mov_b32_e32 v78, v24
	v_mov_b32_e32 v79, v24
	v_mov_b32_e32 v80, v24
	v_mov_b32_e32 v81, v24
	v_mov_b32_e32 v82, v24
	v_mov_b32_e32 v83, v24
	v_mov_b32_e32 v84, v24
	v_mov_b32_e32 v85, v24
	v_mov_b32_e32 v86, v24
	v_mov_b32_e32 v87, v24
	v_mov_b32_e32 v88, v24
	v_mov_b32_e32 v89, v24
	v_mov_b32_e32 v90, v24
	v_mov_b32_e32 v91, v24
	v_mov_b32_e32 v92, v24
	v_mov_b32_e32 v93, v24
	v_mov_b32_e32 v94, v24
	v_mov_b32_e32 v95, v24
	v_lshrrev_b32_e32 v208, 3, v122
	v_xor_b32_e32 v208, v208, v122
	v_and_b32_e32 v208, 7, v208
	v_lshlrev_b32_e32 v208, 4, v208
	v_add_u32_e32 v208, 0xffffff80, v208
	v_mov_b32_e32 v209, -1
	v_lshl_add_u64 v[104:105], v[104:105], 0, v[208:209]
	v_lshl_add_u64 v[106:107], v[106:107], 0, v[208:209]
	v_lshl_add_u64 v[108:109], v[108:109], 0, v[208:209]
	v_lshl_add_u64 v[110:111], v[110:111], 0, v[208:209]
	v_lshl_add_u64 v[112:113], v[112:113], 0, v[208:209]
	v_lshl_add_u64 v[114:115], v[114:115], 0, v[208:209]
	v_lshl_add_u64 v[116:117], v[116:117], 0, v[208:209]
	v_lshl_add_u64 v[118:119], v[118:119], 0, v[208:209]
	v_and_b32_e32 v204, 7, v123
	v_xor_b32_e32 v204, v204, v125
	v_lshlrev_b32_e32 v204, 4, v204
	v_or_b32_e32 v206, v124, v123
	v_lshl_add_u32 v205, v206, 7, v204
	v_and_b32_e32 v206, 0x4f, v122
	v_lshl_add_u32 v206, v206, 7, v204
	v_xor_b32_e32 v207, 64, v206
	v_xor_b32_e32 v204, 64, v205
	v_lshrrev_b32_e32 v208, 6, v122
	s_nop 1
	v_readfirstlane_b32 s56, v208
	s_nop 3
	s_lshl_b32 s56, s56, 10
	s_waitcnt lgkmcnt(0)
	s_barrier
	s_mov_b32 m0, s56
	s_nop 0
	global_load_lds_dwordx4 v[104:105], off
	s_add_u32 m0, s56, 0x1000
	s_nop 0
	global_load_lds_dwordx4 v[106:107], off
	s_add_u32 m0, s56, 0x2000
	s_nop 0
	global_load_lds_dwordx4 v[108:109], off
	s_add_u32 m0, s56, 0x3000
	s_nop 0
	global_load_lds_dwordx4 v[110:111], off
	s_add_u32 m0, s56, 0x4000
	s_nop 0
	global_load_lds_dwordx4 v[112:113], off
	s_add_u32 m0, s56, 0x5000
	s_nop 0
	global_load_lds_dwordx4 v[114:115], off
	s_add_u32 m0, s56, 0x6000
	s_nop 0
	global_load_lds_dwordx4 v[116:117], off
	s_add_u32 m0, s56, 0x7000
	s_nop 0
	global_load_lds_dwordx4 v[118:119], off
	v_lshl_add_u64 v[104:105], v[104:105], 0, s[30:31]
	v_lshl_add_u64 v[106:107], v[106:107], 0, s[30:31]
	v_lshl_add_u64 v[108:109], v[108:109], 0, s[30:31]
	v_lshl_add_u64 v[110:111], v[110:111], 0, s[30:31]
	v_lshl_add_u64 v[112:113], v[112:113], 0, s[30:31]
	v_lshl_add_u64 v[114:115], v[114:115], 0, s[30:31]
	v_lshl_add_u64 v[116:117], v[116:117], 0, s[30:31]
	v_lshl_add_u64 v[118:119], v[118:119], 0, s[30:31]
	s_waitcnt vmcnt(0)
	s_barrier
